# combination: E5 compressed-branch priority 0 + OUT epilogue counted waits vmcnt(7+k) + attention QK K-fragment LDS reads issued early with counted lgkmcnt
# speedup vs baseline: 1.0077x; 1.0022x over previous
.LBB0_506:
	s_or_b64 exec, exec, s[2:3]
	s_mulk_i32 s16, 0x4800
	v_cmp_lt_i32_e32 vcc, 1, v34
	s_and_saveexec_b64 s[2:3], vcc
	s_xor_b64 s[22:23], exec, s[2:3]
	s_cbranch_execz .LBB0_516
	v_cmp_lt_i32_e32 vcc, 2, v34
	s_and_saveexec_b64 s[2:3], vcc
	s_xor_b64 s[2:3], exec, s[2:3]
	s_cbranch_execz .LBB0_511
	v_add3_u32 v124, s16, v100, v116
	s_setprio 1
	ds_read_b128 v[34:37], v124
	ds_read_b128 v[38:41], v124 offset:16
	ds_read_b128 v[42:45], v124 offset:32
	ds_read_b128 v[46:49], v124 offset:48
	v_cmp_lt_i32_e32 vcc, v211, v210
	s_waitcnt lgkmcnt(3)
	v_mfma_f32_32x32x16_bf16 v[50:65], v[34:37], v[78:81], 0
	ds_read_b128 v[34:37], v124 offset:4608
	ds_read_b128 v[120:123], v124 offset:4624
	ds_read_b128 v[126:129], v124 offset:4640
	ds_read_b128 v[130:133], v124 offset:4656
	s_waitcnt lgkmcnt(6)
	v_mfma_f32_32x32x16_bf16 v[50:65], v[38:41], v[74:77], v[50:65]
	s_waitcnt lgkmcnt(5)
	v_mfma_f32_32x32x16_bf16 v[50:65], v[42:45], v[70:73], v[50:65]
	s_waitcnt lgkmcnt(4)
	v_mfma_f32_32x32x16_bf16 v[50:65], v[46:49], v[66:69], v[50:65]
	s_waitcnt lgkmcnt(3)
	v_mfma_f32_32x32x16_bf16 v[34:49], v[34:37], v[78:81], 0
	s_waitcnt lgkmcnt(2)
	v_mfma_f32_32x32x16_bf16 v[34:49], v[120:123], v[74:77], v[34:49]
	s_waitcnt lgkmcnt(1)
	v_mfma_f32_32x32x16_bf16 v[34:49], v[126:129], v[70:73], v[34:49]
	s_waitcnt lgkmcnt(0)
	v_mfma_f32_32x32x16_bf16 v[34:49], v[130:133], v[66:69], v[34:49]
	s_nop 1
	v_max3_f32 v120, v50, s85, v51
	v_max3_f32 v120, v120, v52, v53
	v_max3_f32 v120, v120, v54, v55
	v_max3_f32 v120, v120, v56, v57
	v_max3_f32 v120, v120, v58, v59
	v_max3_f32 v120, v120, v60, v61
	v_max3_f32 v120, v120, v62, v63
	v_max3_f32 v120, v120, v64, v65
	s_nop 1
	v_max3_f32 v120, v120, v34, v35
	v_max3_f32 v120, v120, v36, v37
	v_max3_f32 v120, v120, v38, v39
	v_max3_f32 v120, v120, v40, v41
	v_max3_f32 v120, v120, v42, v43
	v_max3_f32 v120, v120, v44, v45
	v_max3_f32 v120, v120, v46, v47
	v_cndmask_b32_e32 v121, v209, v211, vcc
	v_max3_f32 v120, v120, v48, v49
	v_lshlrev_b32_e32 v121, 2, v121
	ds_bpermute_b32 v121, v121, v120
	s_waitcnt lgkmcnt(0)
	v_max_f32_e32 v121, v121, v121
	v_max_f32_e32 v120, v120, v121
	v_mul_f32_e32 v120, 0x3e38aa3b, v120
	v_cndmask_b32_e64 v120, v220, v120, s[74:75]
	v_add_f32_e32 v121, 0x40c00000, v119
	v_cmp_gt_f32_e32 vcc, v120, v121
	s_cbranch_vccz .LBB0_510
	s_nop 0
	v_cndmask_b32_e32 v121, v119, v120, vcc
	v_sub_f32_e32 v119, v119, v121
	v_exp_f32_e32 v119, v119
	s_nop 0
	v_cndmask_b32_e32 v120, 1.0, v119, vcc
	v_mul_f32_e32 v117, v117, v120
	v_pk_mul_f32 v[32:33], v[32:33], v[120:121] op_sel_hi:[1,0]
	v_pk_mul_f32 v[30:31], v[30:31], v[120:121] op_sel_hi:[1,0]
	v_pk_mul_f32 v[28:29], v[28:29], v[120:121] op_sel_hi:[1,0]
	v_pk_mul_f32 v[26:27], v[26:27], v[120:121] op_sel_hi:[1,0]
	v_pk_mul_f32 v[24:25], v[24:25], v[120:121] op_sel_hi:[1,0]
	v_pk_mul_f32 v[22:23], v[22:23], v[120:121] op_sel_hi:[1,0]
	v_pk_mul_f32 v[20:21], v[20:21], v[120:121] op_sel_hi:[1,0]
	v_pk_mul_f32 v[18:19], v[18:19], v[120:121] op_sel_hi:[1,0]
	v_pk_mul_f32 v[16:17], v[16:17], v[120:121] op_sel_hi:[1,0]
	v_pk_mul_f32 v[14:15], v[14:15], v[120:121] op_sel_hi:[1,0]
	v_pk_mul_f32 v[12:13], v[12:13], v[120:121] op_sel_hi:[1,0]
	v_pk_mul_f32 v[10:11], v[10:11], v[120:121] op_sel_hi:[1,0]
	v_pk_mul_f32 v[8:9], v[8:9], v[120:121] op_sel_hi:[1,0]
	v_pk_mul_f32 v[6:7], v[6:7], v[120:121] op_sel_hi:[1,0]
	v_pk_mul_f32 v[4:5], v[4:5], v[120:121] op_sel_hi:[1,0]
	v_pk_mul_f32 v[2:3], v[2:3], v[120:121] op_sel_hi:[1,0]
	v_mov_b32_e32 v119, v121

.LBB0_511:
	s_andn2_saveexec_b64 s[2:3], s[2:3]
	s_cbranch_execz .LBB0_515
	v_add3_u32 v124, s16, v100, v116
	s_setprio 1
	ds_read_b128 v[34:37], v124
	ds_read_b128 v[50:53], v124 offset:16
	ds_read_b128 v[54:57], v124 offset:32
	ds_read_b128 v[58:61], v124 offset:48
	v_cmp_lt_i32_e32 vcc, -1, v118
	s_waitcnt lgkmcnt(3)
	v_mfma_f32_32x32x16_bf16 v[34:49], v[34:37], v[78:81], 0
	v_cmp_gt_i32_e64 s[38:39], 1, v118
	v_cmp_gt_i32_e64 s[40:41], 32, v118
	v_cmp_gt_i32_e64 s[42:43], 33, v118
	v_cmp_gt_i32_e64 s[44:45], 34, v118
	v_cmp_gt_i32_e64 s[46:47], 35, v118
	v_cmp_gt_i32_e64 s[48:49], 36, v118
	v_cmp_gt_i32_e64 s[50:51], 37, v118
	s_waitcnt lgkmcnt(2)
	v_mfma_f32_32x32x16_bf16 v[34:49], v[50:53], v[74:77], v[34:49]
	ds_read_b128 v[50:53], v124 offset:4608
	ds_read_b128 v[120:123], v124 offset:4624
	ds_read_b128 v[126:129], v124 offset:4640
	ds_read_b128 v[130:133], v124 offset:4656
	v_cmp_gt_i32_e64 s[52:53], 38, v118
	v_cmp_gt_i32_e64 s[56:57], 39, v118
	v_cmp_gt_i32_e64 s[58:59], 48, v118
	v_cmp_gt_i32_e64 s[60:61], 49, v118
	v_cmp_gt_i32_e64 s[62:63], 50, v118
	s_waitcnt lgkmcnt(5)
	v_mfma_f32_32x32x16_bf16 v[34:49], v[54:57], v[70:73], v[34:49]
	v_cmp_gt_i32_e64 s[64:65], 51, v118
	v_cmp_gt_i32_e64 s[66:67], 52, v118
	v_cmp_gt_i32_e64 s[68:69], 53, v118
	v_cmp_gt_i32_e64 s[70:71], 54, v118
	v_cmp_gt_i32_e64 s[54:55], 55, v118
	s_waitcnt lgkmcnt(4)
	v_mfma_f32_32x32x16_bf16 v[34:49], v[58:61], v[66:69], v[34:49]
	s_waitcnt lgkmcnt(3)
	v_mfma_f32_32x32x16_bf16 v[50:65], v[50:53], v[78:81], 0
	s_waitcnt lgkmcnt(2)
	v_mfma_f32_32x32x16_bf16 v[50:65], v[120:123], v[74:77], v[50:65]
	s_waitcnt lgkmcnt(1)
	v_mfma_f32_32x32x16_bf16 v[50:65], v[126:129], v[70:73], v[50:65]
	s_waitcnt lgkmcnt(0)
	v_mfma_f32_32x32x16_bf16 v[50:65], v[130:133], v[66:69], v[50:65]
	s_nop 1
	v_cndmask_b32_e32 v122, v220, v34, vcc
	v_cmp_lt_i32_e32 vcc, 1, v118
	v_cndmask_b32_e64 v120, v35, v220, s[38:39]
	v_max3_f32 v35, v122, s85, v120
	v_cndmask_b32_e32 v36, v220, v36, vcc
	v_cmp_lt_i32_e32 vcc, 2, v118
	s_nop 3
	v_cndmask_b32_e64 v123, v50, v220, s[40:41]
	v_cndmask_b32_e32 v37, v220, v37, vcc
	v_cmp_lt_i32_e32 vcc, 3, v118
	v_max3_f32 v35, v35, v36, v37
	v_cndmask_b32_e64 v124, v51, v220, s[42:43]
	v_cndmask_b32_e32 v121, v220, v38, vcc
	v_cmp_lt_i32_e32 vcc, 4, v118
	v_cndmask_b32_e64 v125, v52, v220, s[44:45]
	v_cndmask_b32_e64 v126, v53, v220, s[46:47]
	v_cndmask_b32_e32 v38, v220, v39, vcc
	v_cmp_lt_i32_e32 vcc, 5, v118
	v_max3_f32 v35, v35, v121, v38
	v_cndmask_b32_e64 v127, v54, v220, s[48:49]
	v_cndmask_b32_e32 v39, v220, v40, vcc
	v_cmp_lt_i32_e32 vcc, 6, v118
	v_cndmask_b32_e64 v128, v55, v220, s[50:51]
	v_cndmask_b32_e64 v130, v56, v220, s[52:53]
	v_cndmask_b32_e32 v40, v220, v41, vcc
	v_cmp_lt_i32_e32 vcc, 15, v118
	v_max3_f32 v35, v35, v39, v40
	v_cndmask_b32_e64 v131, v57, v220, s[56:57]
	v_cndmask_b32_e32 v42, v220, v42, vcc
	v_cmp_lt_i32_e32 vcc, 16, v118
	v_cndmask_b32_e64 v132, v58, v220, s[58:59]
	v_cndmask_b32_e64 v133, v59, v220, s[60:61]
	v_cndmask_b32_e32 v41, v220, v43, vcc
	v_cmp_lt_i32_e32 vcc, 17, v118
	v_max3_f32 v35, v35, v42, v41
	v_cndmask_b32_e64 v134, v60, v220, s[62:63]
	v_cndmask_b32_e32 v43, v220, v44, vcc
	v_cmp_lt_i32_e32 vcc, 18, v118
	v_cndmask_b32_e64 v135, v61, v220, s[64:65]
	v_cndmask_b32_e64 v136, v62, v220, s[66:67]
	v_cndmask_b32_e32 v44, v220, v45, vcc
	v_cmp_lt_i32_e32 vcc, 19, v118
	v_max3_f32 v35, v35, v43, v44
	v_cndmask_b32_e64 v137, v63, v220, s[68:69]
	v_cndmask_b32_e32 v45, v220, v46, vcc
	v_cmp_lt_i32_e32 vcc, 20, v118
	v_cndmask_b32_e64 v129, v64, v220, s[70:71]
	s_nop 0
	v_cndmask_b32_e32 v46, v220, v47, vcc
	v_cmp_lt_i32_e32 vcc, 21, v118
	v_max3_f32 v35, v35, v45, v46
	s_nop 0
	v_cndmask_b32_e32 v47, v220, v48, vcc
	v_cmp_lt_i32_e32 vcc, 22, v118
	s_nop 1
	v_cndmask_b32_e32 v48, v220, v49, vcc
	v_max3_f32 v35, v35, v47, v48
	v_max3_f32 v35, v35, v123, v124
	v_max3_f32 v35, v35, v125, v126
	v_max3_f32 v35, v35, v127, v128
	v_max3_f32 v35, v35, v130, v131
	v_max3_f32 v35, v35, v132, v133
	v_max3_f32 v35, v35, v134, v135
	v_max3_f32 v138, v35, v136, v137
	v_cndmask_b32_e64 v35, v65, v220, s[54:55]
	v_cmp_lt_i32_e32 vcc, v211, v210
	v_max3_f32 v65, v138, v129, v35
	s_nop 0
	v_cndmask_b32_e32 v138, v209, v211, vcc
	v_lshlrev_b32_e32 v138, 2, v138
	ds_bpermute_b32 v138, v138, v65
	s_waitcnt lgkmcnt(0)
	v_max_f32_e32 v138, v138, v138
	v_max_f32_e32 v65, v65, v138
	v_mul_f32_e32 v65, 0x3e38aa3b, v65
	v_add_f32_e32 v138, 0x40c00000, v119
	v_cmp_gt_f32_e32 vcc, v65, v138
	s_cbranch_vccz .LBB0_514
	s_nop 0
	v_cndmask_b32_e32 v65, v119, v65, vcc
	v_sub_f32_e32 v119, v119, v65
	v_exp_f32_e32 v119, v119
	s_nop 0
	v_cndmask_b32_e32 v138, 1.0, v119, vcc
	v_mul_f32_e32 v117, v117, v138
	v_pk_mul_f32 v[32:33], v[32:33], v[138:139] op_sel_hi:[1,0]
	v_pk_mul_f32 v[30:31], v[30:31], v[138:139] op_sel_hi:[1,0]
	v_pk_mul_f32 v[28:29], v[28:29], v[138:139] op_sel_hi:[1,0]
	v_pk_mul_f32 v[26:27], v[26:27], v[138:139] op_sel_hi:[1,0]
	v_pk_mul_f32 v[24:25], v[24:25], v[138:139] op_sel_hi:[1,0]
	v_pk_mul_f32 v[22:23], v[22:23], v[138:139] op_sel_hi:[1,0]
	v_pk_mul_f32 v[20:21], v[20:21], v[138:139] op_sel_hi:[1,0]
	v_pk_mul_f32 v[18:19], v[18:19], v[138:139] op_sel_hi:[1,0]
	v_pk_mul_f32 v[16:17], v[16:17], v[138:139] op_sel_hi:[1,0]
	v_pk_mul_f32 v[14:15], v[14:15], v[138:139] op_sel_hi:[1,0]
	v_pk_mul_f32 v[12:13], v[12:13], v[138:139] op_sel_hi:[1,0]
	v_pk_mul_f32 v[10:11], v[10:11], v[138:139] op_sel_hi:[1,0]
	v_pk_mul_f32 v[8:9], v[8:9], v[138:139] op_sel_hi:[1,0]
	v_pk_mul_f32 v[6:7], v[6:7], v[138:139] op_sel_hi:[1,0]
	v_pk_mul_f32 v[4:5], v[4:5], v[138:139] op_sel_hi:[1,0]
	v_pk_mul_f32 v[2:3], v[2:3], v[138:139] op_sel_hi:[1,0]
	v_mov_b32_e32 v119, v65

.LBB0_516:
	s_andn2_saveexec_b64 s[22:23], s[22:23]
	s_cbranch_execz .LBB0_522
	v_cmp_eq_u32_e32 vcc, 1, v34
	s_and_saveexec_b64 s[2:3], vcc
	s_cbranch_execz .LBB0_521
	v_add3_u32 v124, s16, v100, v116
	s_setprio 1
	ds_read_b128 v[34:37], v124
	ds_read_b128 v[38:41], v124 offset:16
	ds_read_b128 v[42:45], v124 offset:32
	ds_read_b128 v[46:49], v124 offset:48
	v_cmp_lt_i32_e32 vcc, v211, v210
	s_waitcnt lgkmcnt(3)
	v_mfma_f32_32x32x16_bf16 v[50:65], v[34:37], v[78:81], 0
	ds_read_b128 v[34:37], v124 offset:4608
	ds_read_b128 v[120:123], v124 offset:4624
	ds_read_b128 v[126:129], v124 offset:4640
	ds_read_b128 v[130:133], v124 offset:4656
	s_waitcnt lgkmcnt(6)
	v_mfma_f32_32x32x16_bf16 v[50:65], v[38:41], v[74:77], v[50:65]
	s_waitcnt lgkmcnt(5)
	v_mfma_f32_32x32x16_bf16 v[50:65], v[42:45], v[70:73], v[50:65]
	s_waitcnt lgkmcnt(4)
	v_mfma_f32_32x32x16_bf16 v[50:65], v[46:49], v[66:69], v[50:65]
	s_waitcnt lgkmcnt(3)
	v_mfma_f32_32x32x16_bf16 v[34:49], v[34:37], v[78:81], 0
	s_waitcnt lgkmcnt(2)
	v_mfma_f32_32x32x16_bf16 v[34:49], v[120:123], v[74:77], v[34:49]
	s_waitcnt lgkmcnt(1)
	v_mfma_f32_32x32x16_bf16 v[34:49], v[126:129], v[70:73], v[34:49]
	s_waitcnt lgkmcnt(0)
	v_mfma_f32_32x32x16_bf16 v[34:49], v[130:133], v[66:69], v[34:49]
	s_nop 1
	v_max3_f32 v120, v50, s85, v51
	v_max3_f32 v120, v120, v52, v53
	v_max3_f32 v120, v120, v54, v55
	v_max3_f32 v120, v120, v56, v57
	v_max3_f32 v120, v120, v58, v59
	v_max3_f32 v120, v120, v60, v61
	v_max3_f32 v120, v120, v62, v63
	v_max3_f32 v120, v120, v64, v65
	s_nop 1
	v_max3_f32 v120, v120, v34, v35
	v_max3_f32 v120, v120, v36, v37
	v_max3_f32 v120, v120, v38, v39
	v_max3_f32 v120, v120, v40, v41
	v_max3_f32 v120, v120, v42, v43
	v_max3_f32 v120, v120, v44, v45
	v_max3_f32 v120, v120, v46, v47
	v_cndmask_b32_e32 v121, v209, v211, vcc
	v_max3_f32 v120, v120, v48, v49
	v_lshlrev_b32_e32 v121, 2, v121
	ds_bpermute_b32 v121, v121, v120
	s_waitcnt lgkmcnt(0)
	v_max_f32_e32 v121, v121, v121
	v_max_f32_e32 v120, v120, v121
	v_mul_f32_e32 v120, 0x3e38aa3b, v120
	v_add_f32_e32 v121, 0x40c00000, v119
	v_cmp_gt_f32_e32 vcc, v120, v121
	s_cbranch_vccz .LBB0_520
	s_nop 0
	v_cndmask_b32_e32 v121, v119, v120, vcc
	v_sub_f32_e32 v119, v119, v121
	v_exp_f32_e32 v119, v119
	s_nop 0
	v_cndmask_b32_e32 v120, 1.0, v119, vcc
	v_mul_f32_e32 v117, v117, v120
	v_pk_mul_f32 v[32:33], v[32:33], v[120:121] op_sel_hi:[1,0]
	v_pk_mul_f32 v[30:31], v[30:31], v[120:121] op_sel_hi:[1,0]
	v_pk_mul_f32 v[28:29], v[28:29], v[120:121] op_sel_hi:[1,0]
	v_pk_mul_f32 v[26:27], v[26:27], v[120:121] op_sel_hi:[1,0]
	v_pk_mul_f32 v[24:25], v[24:25], v[120:121] op_sel_hi:[1,0]
	v_pk_mul_f32 v[22:23], v[22:23], v[120:121] op_sel_hi:[1,0]
	v_pk_mul_f32 v[20:21], v[20:21], v[120:121] op_sel_hi:[1,0]
	v_pk_mul_f32 v[18:19], v[18:19], v[120:121] op_sel_hi:[1,0]
	v_pk_mul_f32 v[16:17], v[16:17], v[120:121] op_sel_hi:[1,0]
	v_pk_mul_f32 v[14:15], v[14:15], v[120:121] op_sel_hi:[1,0]
	v_pk_mul_f32 v[12:13], v[12:13], v[120:121] op_sel_hi:[1,0]
	v_pk_mul_f32 v[10:11], v[10:11], v[120:121] op_sel_hi:[1,0]
	v_pk_mul_f32 v[8:9], v[8:9], v[120:121] op_sel_hi:[1,0]
	v_pk_mul_f32 v[6:7], v[6:7], v[120:121] op_sel_hi:[1,0]
	v_pk_mul_f32 v[4:5], v[4:5], v[120:121] op_sel_hi:[1,0]
	v_pk_mul_f32 v[2:3], v[2:3], v[120:121] op_sel_hi:[1,0]
	v_mov_b32_e32 v119, v121

.LBB0_608:
	s_and_b64 vcc, exec, s[2:3]
	s_cbranch_vccz .LBB0_614
	s_cmp_lg_u32 s76, 1
	s_cbranch_scc1 .LBB0_613
	v_add3_u32 v70, s37, v136, v139
	s_nop 6
	s_setprio 1
	ds_read_b128 v[34:37], v70
	ds_read_b128 v[38:41], v70 offset:16
	ds_read_b128 v[42:45], v70 offset:32
	ds_read_b128 v[46:49], v70 offset:48
	v_cmp_lt_i32_e32 vcc, v211, v210
	s_waitcnt lgkmcnt(3)
	v_mfma_f32_32x32x16_bf16 v[50:65], v[34:37], v[98:101], 0
	ds_read_b128 v[34:37], v70 offset:4608
	ds_read_b128 v[66:69], v70 offset:4624
	ds_read_b128 v[72:75], v70 offset:4640
	s_waitcnt lgkmcnt(5)
	v_mfma_f32_32x32x16_bf16 v[50:65], v[38:41], v[102:105], v[50:65]
	s_waitcnt lgkmcnt(4)
	v_mfma_f32_32x32x16_bf16 v[50:65], v[42:45], v[106:109], v[50:65]
	s_waitcnt lgkmcnt(3)
	v_mfma_f32_32x32x16_bf16 v[50:65], v[46:49], v[110:113], v[50:65]
	s_waitcnt lgkmcnt(2)
	v_mfma_f32_32x32x16_bf16 v[34:49], v[34:37], v[98:101], 0
	s_waitcnt lgkmcnt(1)
	v_mfma_f32_32x32x16_bf16 v[34:49], v[66:69], v[102:105], v[34:49]
	ds_read_b128 v[66:69], v70 offset:4656
	s_waitcnt lgkmcnt(1)
	v_mfma_f32_32x32x16_bf16 v[34:49], v[72:75], v[106:109], v[34:49]
	s_waitcnt lgkmcnt(0)
	v_mfma_f32_32x32x16_bf16 v[34:49], v[66:69], v[110:113], v[34:49]
	s_nop 1
	v_max3_f32 v66, v50, s85, v51
	v_max3_f32 v66, v66, v52, v53
	v_max3_f32 v66, v66, v54, v55
	v_max3_f32 v66, v66, v56, v57
	v_max3_f32 v66, v66, v58, v59
	v_max3_f32 v66, v66, v60, v61
	v_max3_f32 v66, v66, v62, v63
	v_max3_f32 v66, v66, v64, v65
	s_nop 1
	v_max3_f32 v66, v66, v34, v35
	v_max3_f32 v66, v66, v36, v37
	v_max3_f32 v66, v66, v38, v39
	v_max3_f32 v66, v66, v40, v41
	v_max3_f32 v66, v66, v42, v43
	v_max3_f32 v66, v66, v44, v45
	v_max3_f32 v66, v66, v46, v47
	v_cndmask_b32_e32 v67, v209, v211, vcc
	v_max3_f32 v66, v66, v48, v49
	v_lshlrev_b32_e32 v67, 2, v67
	ds_bpermute_b32 v67, v67, v66
	s_waitcnt lgkmcnt(0)
	v_max_f32_e32 v67, v67, v67
	v_max_f32_e32 v66, v66, v67
	v_mul_f32_e32 v66, 0x3e38aa3b, v66
	v_add_f32_e32 v67, 0x40c00000, v152
	v_cmp_gt_f32_e32 vcc, v66, v67
	s_cbranch_vccz .LBB0_612
	s_nop 0
	v_cndmask_b32_e32 v67, v152, v66, vcc
	v_sub_f32_e32 v66, v152, v67
	v_exp_f32_e32 v66, v66
	v_mov_b32_e32 v152, v67
	v_cndmask_b32_e32 v66, 1.0, v66, vcc
	v_mul_f32_e32 v133, v133, v66
	v_pk_mul_f32 v[16:17], v[16:17], v[66:67] op_sel_hi:[1,0]
	v_pk_mul_f32 v[14:15], v[14:15], v[66:67] op_sel_hi:[1,0]
	v_pk_mul_f32 v[12:13], v[12:13], v[66:67] op_sel_hi:[1,0]
	v_pk_mul_f32 v[10:11], v[10:11], v[66:67] op_sel_hi:[1,0]
	v_pk_mul_f32 v[8:9], v[8:9], v[66:67] op_sel_hi:[1,0]
	v_pk_mul_f32 v[6:7], v[6:7], v[66:67] op_sel_hi:[1,0]
	v_pk_mul_f32 v[4:5], v[4:5], v[66:67] op_sel_hi:[1,0]
	v_pk_mul_f32 v[2:3], v[2:3], v[66:67] op_sel_hi:[1,0]
	v_pk_mul_f32 v[32:33], v[32:33], v[66:67] op_sel_hi:[1,0]
	v_pk_mul_f32 v[30:31], v[30:31], v[66:67] op_sel_hi:[1,0]
	v_pk_mul_f32 v[28:29], v[28:29], v[66:67] op_sel_hi:[1,0]
	v_pk_mul_f32 v[26:27], v[26:27], v[66:67] op_sel_hi:[1,0]
	v_pk_mul_f32 v[24:25], v[24:25], v[66:67] op_sel_hi:[1,0]
	v_pk_mul_f32 v[22:23], v[22:23], v[66:67] op_sel_hi:[1,0]
	v_pk_mul_f32 v[20:21], v[20:21], v[66:67] op_sel_hi:[1,0]
	v_pk_mul_f32 v[18:19], v[18:19], v[66:67] op_sel_hi:[1,0]

.LBB0_654:
	s_and_b64 vcc, exec, s[2:3]
	s_cbranch_vccz .LBB0_660
	s_cmp_lg_u32 s76, 1
	s_cbranch_scc1 .LBB0_659
	v_add3_u32 v70, s37, v136, v139
	s_nop 6
	s_setprio 1
	ds_read_b128 v[34:37], v70
	ds_read_b128 v[38:41], v70 offset:16
	ds_read_b128 v[42:45], v70 offset:32
	ds_read_b128 v[46:49], v70 offset:48
	v_cmp_lt_i32_e32 vcc, v211, v210
	s_waitcnt lgkmcnt(3)
	v_mfma_f32_32x32x16_bf16 v[50:65], v[34:37], v[98:101], 0
	ds_read_b128 v[34:37], v70 offset:4608
	ds_read_b128 v[66:69], v70 offset:4624
	ds_read_b128 v[72:75], v70 offset:4640
	ds_read_b128 v[76:79], v70 offset:4656
	s_waitcnt lgkmcnt(6)
	v_mfma_f32_32x32x16_bf16 v[50:65], v[38:41], v[102:105], v[50:65]
	s_waitcnt lgkmcnt(5)
	v_mfma_f32_32x32x16_bf16 v[50:65], v[42:45], v[106:109], v[50:65]
	s_waitcnt lgkmcnt(4)
	v_mfma_f32_32x32x16_bf16 v[50:65], v[46:49], v[110:113], v[50:65]
	s_waitcnt lgkmcnt(3)
	v_mfma_f32_32x32x16_bf16 v[34:49], v[34:37], v[98:101], 0
	s_waitcnt lgkmcnt(2)
	v_mfma_f32_32x32x16_bf16 v[34:49], v[66:69], v[102:105], v[34:49]
	s_waitcnt lgkmcnt(1)
	v_mfma_f32_32x32x16_bf16 v[34:49], v[72:75], v[106:109], v[34:49]
	s_waitcnt lgkmcnt(0)
	v_mfma_f32_32x32x16_bf16 v[34:49], v[76:79], v[110:113], v[34:49]
	s_nop 1
	v_max3_f32 v66, v50, s85, v51
	v_max3_f32 v66, v66, v52, v53
	v_max3_f32 v66, v66, v54, v55
	v_max3_f32 v66, v66, v56, v57
	v_max3_f32 v66, v66, v58, v59
	v_max3_f32 v66, v66, v60, v61
	v_max3_f32 v66, v66, v62, v63
	v_max3_f32 v66, v66, v64, v65
	s_nop 1
	v_max3_f32 v66, v66, v34, v35
	v_max3_f32 v66, v66, v36, v37
	v_max3_f32 v66, v66, v38, v39
	v_max3_f32 v66, v66, v40, v41
	v_max3_f32 v66, v66, v42, v43
	v_max3_f32 v66, v66, v44, v45
	v_max3_f32 v66, v66, v46, v47
	v_cndmask_b32_e32 v67, v209, v211, vcc
	v_max3_f32 v66, v66, v48, v49
	v_lshlrev_b32_e32 v67, 2, v67
	ds_bpermute_b32 v67, v67, v66
	s_waitcnt lgkmcnt(0)
	v_max_f32_e32 v67, v67, v67
	v_max_f32_e32 v66, v66, v67
	v_mul_f32_e32 v66, 0x3e38aa3b, v66
	v_add_f32_e32 v67, 0x40c00000, v152
	v_cmp_gt_f32_e32 vcc, v66, v67
	s_cbranch_vccz .LBB0_658
	s_nop 0
	v_cndmask_b32_e32 v67, v152, v66, vcc
	v_sub_f32_e32 v66, v152, v67
	v_exp_f32_e32 v66, v66
	v_mov_b32_e32 v152, v67
	v_cndmask_b32_e32 v66, 1.0, v66, vcc
	v_mul_f32_e32 v133, v133, v66
	v_pk_mul_f32 v[16:17], v[16:17], v[66:67] op_sel_hi:[1,0]
	v_pk_mul_f32 v[14:15], v[14:15], v[66:67] op_sel_hi:[1,0]
	v_pk_mul_f32 v[12:13], v[12:13], v[66:67] op_sel_hi:[1,0]
	v_pk_mul_f32 v[10:11], v[10:11], v[66:67] op_sel_hi:[1,0]
	v_pk_mul_f32 v[8:9], v[8:9], v[66:67] op_sel_hi:[1,0]
	v_pk_mul_f32 v[6:7], v[6:7], v[66:67] op_sel_hi:[1,0]
	v_pk_mul_f32 v[4:5], v[4:5], v[66:67] op_sel_hi:[1,0]
	v_pk_mul_f32 v[2:3], v[2:3], v[66:67] op_sel_hi:[1,0]
	v_pk_mul_f32 v[32:33], v[32:33], v[66:67] op_sel_hi:[1,0]
	v_pk_mul_f32 v[30:31], v[30:31], v[66:67] op_sel_hi:[1,0]
	v_pk_mul_f32 v[28:29], v[28:29], v[66:67] op_sel_hi:[1,0]
	v_pk_mul_f32 v[26:27], v[26:27], v[66:67] op_sel_hi:[1,0]
	v_pk_mul_f32 v[24:25], v[24:25], v[66:67] op_sel_hi:[1,0]
	v_pk_mul_f32 v[22:23], v[22:23], v[66:67] op_sel_hi:[1,0]
	v_pk_mul_f32 v[20:21], v[20:21], v[66:67] op_sel_hi:[1,0]
	v_pk_mul_f32 v[18:19], v[18:19], v[66:67] op_sel_hi:[1,0]

.LBB0_762:
	s_and_b64 vcc, exec, s[2:3]
	s_cbranch_vccz .LBB0_768
	s_cmp_lg_u32 s16, 1
	s_cbranch_scc1 .LBB0_767
	v_add3_u32 v70, s76, v132, v137
	s_setprio 1
	ds_read_b128 v[34:37], v70
	ds_read_b128 v[38:41], v70 offset:16
	ds_read_b128 v[42:45], v70 offset:32
	ds_read_b128 v[46:49], v70 offset:48
	v_cmp_lt_i32_e32 vcc, v211, v210
	s_waitcnt lgkmcnt(3)
	v_mfma_f32_32x32x16_bf16 v[50:65], v[34:37], v[98:101], 0
	ds_read_b128 v[34:37], v70 offset:4608
	ds_read_b128 v[66:69], v70 offset:4624
	ds_read_b128 v[72:75], v70 offset:4640
	s_waitcnt lgkmcnt(5)
	v_mfma_f32_32x32x16_bf16 v[50:65], v[38:41], v[102:105], v[50:65]
	s_waitcnt lgkmcnt(4)
	v_mfma_f32_32x32x16_bf16 v[50:65], v[42:45], v[106:109], v[50:65]
	s_waitcnt lgkmcnt(3)
	v_mfma_f32_32x32x16_bf16 v[50:65], v[46:49], v[110:113], v[50:65]
	s_waitcnt lgkmcnt(2)
	v_mfma_f32_32x32x16_bf16 v[34:49], v[34:37], v[98:101], 0
	s_waitcnt lgkmcnt(1)
	v_mfma_f32_32x32x16_bf16 v[34:49], v[66:69], v[102:105], v[34:49]
	ds_read_b128 v[66:69], v70 offset:4656
	s_waitcnt lgkmcnt(1)
	v_mfma_f32_32x32x16_bf16 v[34:49], v[72:75], v[106:109], v[34:49]
	s_waitcnt lgkmcnt(0)
	v_mfma_f32_32x32x16_bf16 v[34:49], v[66:69], v[110:113], v[34:49]
	s_nop 1
	v_max3_f32 v66, v50, s85, v51
	v_max3_f32 v66, v66, v52, v53
	v_max3_f32 v66, v66, v54, v55
	v_max3_f32 v66, v66, v56, v57
	v_max3_f32 v66, v66, v58, v59
	v_max3_f32 v66, v66, v60, v61
	v_max3_f32 v66, v66, v62, v63
	v_max3_f32 v66, v66, v64, v65
	s_nop 1
	v_max3_f32 v66, v66, v34, v35
	v_max3_f32 v66, v66, v36, v37
	v_max3_f32 v66, v66, v38, v39
	v_max3_f32 v66, v66, v40, v41
	v_max3_f32 v66, v66, v42, v43
	v_max3_f32 v66, v66, v44, v45
	v_max3_f32 v66, v66, v46, v47
	v_cndmask_b32_e32 v67, v209, v211, vcc
	v_max3_f32 v66, v66, v48, v49
	v_lshlrev_b32_e32 v67, 2, v67
	ds_bpermute_b32 v67, v67, v66
	s_waitcnt lgkmcnt(0)
	v_max_f32_e32 v67, v67, v67
	v_max_f32_e32 v66, v66, v67
	v_mul_f32_e32 v66, 0x3e38aa3b, v66
	v_add_f32_e32 v67, 0x40c00000, v152
	v_cmp_gt_f32_e32 vcc, v66, v67
	s_cbranch_vccz .LBB0_766
	s_nop 0
	v_cndmask_b32_e32 v67, v152, v66, vcc
	v_sub_f32_e32 v66, v152, v67
	v_exp_f32_e32 v66, v66
	v_mov_b32_e32 v152, v67
	v_cndmask_b32_e32 v66, 1.0, v66, vcc
	v_mul_f32_e32 v151, v151, v66
	v_pk_mul_f32 v[16:17], v[16:17], v[66:67] op_sel_hi:[1,0]
	v_pk_mul_f32 v[14:15], v[14:15], v[66:67] op_sel_hi:[1,0]
	v_pk_mul_f32 v[12:13], v[12:13], v[66:67] op_sel_hi:[1,0]
	v_pk_mul_f32 v[10:11], v[10:11], v[66:67] op_sel_hi:[1,0]
	v_pk_mul_f32 v[8:9], v[8:9], v[66:67] op_sel_hi:[1,0]
	v_pk_mul_f32 v[6:7], v[6:7], v[66:67] op_sel_hi:[1,0]
	v_pk_mul_f32 v[4:5], v[4:5], v[66:67] op_sel_hi:[1,0]
	v_pk_mul_f32 v[2:3], v[2:3], v[66:67] op_sel_hi:[1,0]
	v_pk_mul_f32 v[32:33], v[32:33], v[66:67] op_sel_hi:[1,0]
	v_pk_mul_f32 v[30:31], v[30:31], v[66:67] op_sel_hi:[1,0]
	v_pk_mul_f32 v[28:29], v[28:29], v[66:67] op_sel_hi:[1,0]
	v_pk_mul_f32 v[26:27], v[26:27], v[66:67] op_sel_hi:[1,0]
	v_pk_mul_f32 v[24:25], v[24:25], v[66:67] op_sel_hi:[1,0]
	v_pk_mul_f32 v[22:23], v[22:23], v[66:67] op_sel_hi:[1,0]
	v_pk_mul_f32 v[20:21], v[20:21], v[66:67] op_sel_hi:[1,0]
	v_pk_mul_f32 v[18:19], v[18:19], v[66:67] op_sel_hi:[1,0]

.LBB0_934:
	s_andn2_b64 vcc, exec, s[2:3]
	s_cbranch_vccnz .LBB0_940
	s_cmp_lg_u32 s76, 1
	s_cbranch_scc1 .LBB0_939
	v_add3_u32 v102, s23, v170, v173
	s_setprio 1
	ds_read_b128 v[66:69], v102
	ds_read_b128 v[70:73], v102 offset:16
	ds_read_b128 v[74:77], v102 offset:32
	ds_read_b128 v[78:81], v102 offset:48
	s_waitcnt lgkmcnt(3)
	v_mfma_f32_32x32x16_bf16 v[82:97], v[66:69], v[130:133], 0
	ds_read_b128 v[66:69], v102 offset:4608
	ds_read_b128 v[98:101], v102 offset:4624
	ds_read_b128 v[104:107], v102 offset:4640
	s_waitcnt lgkmcnt(5)
	v_mfma_f32_32x32x16_bf16 v[82:97], v[70:73], v[134:137], v[82:97]
	s_waitcnt lgkmcnt(4)
	v_mfma_f32_32x32x16_bf16 v[82:97], v[74:77], v[138:141], v[82:97]
	s_waitcnt lgkmcnt(3)
	v_mfma_f32_32x32x16_bf16 v[82:97], v[78:81], v[142:145], v[82:97]
	s_waitcnt lgkmcnt(2)
	v_mfma_f32_32x32x16_bf16 v[66:81], v[66:69], v[130:133], 0
	s_waitcnt lgkmcnt(1)
	v_mfma_f32_32x32x16_bf16 v[66:81], v[98:101], v[134:137], v[66:81]
	ds_read_b128 v[98:101], v102 offset:4656
	s_waitcnt lgkmcnt(1)
	v_mfma_f32_32x32x16_bf16 v[66:81], v[104:107], v[138:141], v[66:81]
	s_waitcnt lgkmcnt(0)
	v_mfma_f32_32x32x16_bf16 v[66:81], v[98:101], v[142:145], v[66:81]
	s_nop 1
	v_max3_f32 v98, v82, s85, v83
	v_max3_f32 v98, v98, v84, v85
	v_max3_f32 v98, v98, v86, v87
	v_max3_f32 v98, v98, v88, v89
	v_max3_f32 v98, v98, v90, v91
	v_max3_f32 v98, v98, v92, v93
	v_max3_f32 v98, v98, v94, v95
	v_max3_f32 v98, v98, v96, v97
	s_nop 1
	v_max3_f32 v98, v98, v66, v67
	v_max3_f32 v98, v98, v68, v69
	v_max3_f32 v98, v98, v70, v71
	v_max3_f32 v98, v98, v72, v73
	v_max3_f32 v98, v98, v74, v75
	v_max3_f32 v98, v98, v76, v77
	v_max3_f32 v98, v98, v78, v79
	v_max3_f32 v98, v98, v80, v81
	ds_bpermute_b32 v99, v167, v98
	s_waitcnt lgkmcnt(0)
	v_max_f32_e32 v99, v99, v99
	v_max_f32_e32 v98, v98, v99
	v_mul_f32_e32 v98, 0x3e38aa3b, v98
	v_add_f32_e32 v99, 0x40c00000, v189
	v_cmp_gt_f32_e32 vcc, v98, v99
	s_cbranch_vccz .LBB0_938
	s_nop 0
	v_cndmask_b32_e32 v99, v189, v98, vcc
	v_sub_f32_e32 v98, v189, v99
	v_exp_f32_e32 v98, v98
	v_mov_b32_e32 v189, v99
	v_cndmask_b32_e32 v98, 1.0, v98, vcc
	v_mul_f32_e32 v188, v188, v98
	v_pk_mul_f32 v[48:49], v[48:49], v[98:99] op_sel_hi:[1,0]
	v_pk_mul_f32 v[46:47], v[46:47], v[98:99] op_sel_hi:[1,0]
	v_pk_mul_f32 v[44:45], v[44:45], v[98:99] op_sel_hi:[1,0]
	v_pk_mul_f32 v[42:43], v[42:43], v[98:99] op_sel_hi:[1,0]
	v_pk_mul_f32 v[40:41], v[40:41], v[98:99] op_sel_hi:[1,0]
	v_pk_mul_f32 v[38:39], v[38:39], v[98:99] op_sel_hi:[1,0]
	v_pk_mul_f32 v[36:37], v[36:37], v[98:99] op_sel_hi:[1,0]
	v_pk_mul_f32 v[34:35], v[34:35], v[98:99] op_sel_hi:[1,0]
	v_pk_mul_f32 v[64:65], v[64:65], v[98:99] op_sel_hi:[1,0]
	v_pk_mul_f32 v[62:63], v[62:63], v[98:99] op_sel_hi:[1,0]
	v_pk_mul_f32 v[60:61], v[60:61], v[98:99] op_sel_hi:[1,0]
	v_pk_mul_f32 v[58:59], v[58:59], v[98:99] op_sel_hi:[1,0]
	v_pk_mul_f32 v[56:57], v[56:57], v[98:99] op_sel_hi:[1,0]
	v_pk_mul_f32 v[54:55], v[54:55], v[98:99] op_sel_hi:[1,0]
	v_pk_mul_f32 v[52:53], v[52:53], v[98:99] op_sel_hi:[1,0]
	v_pk_mul_f32 v[50:51], v[50:51], v[98:99] op_sel_hi:[1,0]
